# idle partner workgroup on scan CUs polls with s_sleep 127 instead of 16 (less issue interference with the scan wave), on v40
# speedup vs baseline: 1.0090x; 1.0043x over previous
.Lmix_sec_wait:
	global_load_dword v3, v2, s[12:13] sc1
	s_waitcnt vmcnt(0)
	v_readfirstlane_b32 s8, v3
	s_lshr_b32 s8, s8, 24
	s_cmp_lg_u32 s8, 0
	s_cbranch_scc1 .Lmix_sec_done
	s_sleep 127
	s_add_i32 s2, s2, 1
	s_cmp_lt_u32 s2, 0x1000
	s_cbranch_scc1 .Lmix_sec_wait
